# v83 + entry-sync poll load issued before the end-of-P0 drain (checked at B1, loop only if unreleased)
# speedup vs baseline: 1.0004x; 1.0004x over previous
; __device__ __forceinline__ void xcd_barrier(const XcdBarrier& b) {
;     asm volatile("s_waitcnt vmcnt(0)" ::: "memory");
;     __syncthreads();
;     if (threadIdx.x == 0) {
;         unsigned* bar = b.bar;
;         __builtin_amdgcn_s_waitcnt(0);
;         unsigned nloc = b.st[0], nx = b.st[1];
;         if (nloc == 0u) { xcd_barrier_complete(bar, b.x, nloc, nx); b.st[0] = nloc; b.st[1] = nx; }
.LBB0_109:
	v_readlane_b32 s2, v254, 35
	v_readlane_b32 s3, v254, 36
	s_nop 3
	s_cmp_eq_u64 s[2:3], 0
	s_cbranch_scc1 .Lcgpre_skip
	v_readlane_b32 s2, v255, 41
	v_readlane_b32 s3, v255, 42
	v_mov_b32_e32 v100, 0
	s_nop 4
	global_load_dword v101, v100, s[2:3] offset:32 sc1
.Lcgpre_skip:
	s_waitcnt vmcnt(0)
	s_barrier
	s_mov_b64 s[0:1], exec
	v_readlane_b32 s2, v254, 35
	v_readlane_b32 s3, v254, 36
	s_and_b64 s[2:3], s[0:1], s[2:3]
	s_mov_b64 exec, s[2:3]
	s_cbranch_execz .LBB0_161
	v_readlane_b32 s2, v255, 41
	v_readlane_b32 s3, v255, 42
	v_readlane_b32 s100, v255, 40
	v_mov_b32_e32 v0, 0
	s_nop 4
	v_and_b32_e32 v2, 0xffff0000, v101
	v_cmp_ne_u32_e32 vcc, s100, v2
	s_cbranch_vccnz .Lcgw_done
